# v15: GEMM epilogue stores transposed through a 1 KB/wave LDS buffer so 4 lanes write 64 contiguous bytes (4x fewer L1 requests), read-back pipelined under the next payload's VALU; both GEMM instances
# speedup vs baseline: 1.1007x; 1.0033x over previous
; __device__ __forceinline__ unsigned cvt_pk_bf16(float lo, float hi) { unsigned r; asm volatile("v_cvt_pk_bf16_f32 %0, %1, %2" : "=v"(r) : "v"(lo), "v"(hi)); return r; }
; __device__ __forceinline__ float relu_sq(float x) { float r; asm volatile("v_max_f32 %0, 0, %1" : "=v"(r) : "v"(x)); return r * r; }
;     __device__ __forceinline__ void operator()(const f32x4 (&acc)[2][2][4][2], const Unit& u, int wr, int wc, int fr, int fq) const {
;     ...
;             for (int m = 0; m < 4; ++m) { const int row_ = row0 + ai * HALF + m * 16; bf16_t* rowp = O + (size_t)(row_ >> 11) * gs + (size_t)(row_ & 2047) * ldc + col0; const float sc = rs ? rs[row0 + ai * HALF + m * 16] : 1.f;
; #pragma unroll
;                 for (int bj = 0; bj < 2; ++bj) { f32x4 v0 = acc[ai][bj][m][0] * sc, v1 = acc[ai][bj][m][1] * sc;
;                     if (ACT == 1) {
; #pragma unroll
;                         for (int e = 0; e < 4; ++e) { v0[e] = relu_sq(v0[e]); v1[e] = relu_sq(v1[e]); } }
;                     u32x4 w; w.x = cvt_pk_bf16(v0[0], v0[1]); w.y = cvt_pk_bf16(v0[2], v0[3]); w.z = cvt_pk_bf16(v1[0], v1[1]); w.w = cvt_pk_bf16(v1[2], v1[3]);
;                     *(u32x4*)(rowp + bj * HALF) = w; } }
.LBB0_473:
	v_bitop3_b32 v128, v150, v184, v150 bitop3:0xc8
	s_ashr_i32 s41, s41, 11
	s_mul_hi_i32 s43, s26, s41
	s_mul_i32 s42, s26, s41
	s_lshl_b64 s[42:43], s[42:43], 1
	v_lshl_or_b32 v148, s88, 8, v152
	s_add_u32 s88, s12, s42
	v_mul_u32_u24_e32 v128, s39, v128
	s_addc_u32 s89, s13, s43
	v_lshlrev_b32_e32 v128, 1, v128
	v_ashrrev_i32_e32 v149, 31, v148
	v_lshl_add_u64 v[158:159], s[88:89], 0, v[128:129]
	v_lshl_add_u64 v[158:159], v[148:149], 1, v[158:159]
	s_waitcnt vmcnt(0)
	v_pk_mul_f32 v[126:127], v[126:127], v[200:201] op_sel_hi:[1,0]
	v_pk_mul_f32 v[124:125], v[124:125], v[200:201] op_sel_hi:[1,0]
	v_pk_mul_f32 v[160:161], v[122:123], v[200:201] op_sel_hi:[1,0]
	v_pk_mul_f32 v[122:123], v[120:121], v[200:201] op_sel_hi:[1,0]
	v_cvt_pk_bf16_f32 v120, v124, v125
	v_cvt_pk_bf16_f32 v121, v126, v127
	s_nop 0
	v_cvt_pk_bf16_f32 v122, v122, v123
	v_cvt_pk_bf16_f32 v123, v160, v161
	ds_write_b128 v154, v[120:123]
	ds_read_b128 v[216:219], v187
	s_nop 1
	v_pk_mul_f32 v[118:119], v[118:119], v[200:201] op_sel_hi:[1,0]
	v_pk_mul_f32 v[116:117], v[116:117], v[200:201] op_sel_hi:[1,0]
	v_pk_mul_f32 v[120:121], v[114:115], v[200:201] op_sel_hi:[1,0]
	v_pk_mul_f32 v[114:115], v[112:113], v[200:201] op_sel_hi:[1,0]
	v_cvt_pk_bf16_f32 v112, v116, v117
	v_cvt_pk_bf16_f32 v113, v118, v119
	s_nop 0
	v_cvt_pk_bf16_f32 v114, v114, v115
	v_cvt_pk_bf16_f32 v115, v120, v121
	s_waitcnt lgkmcnt(0)
	global_store_dwordx4 v[158:159], v[216:219], off
	ds_write_b128 v154, v[112:115]
	ds_read_b128 v[216:219], v187
	s_nop 1
	s_nop 0
.LBB0_475:
	s_movk_i32 s41, 0x7df
	v_bitop3_b32 v112, v150, s41, 16 bitop3:0xc8
	v_mul_u32_u24_e32 v112, s39, v112
	v_lshlrev_b32_e32 v128, 1, v112
	v_lshl_add_u64 v[112:113], s[88:89], 0, v[128:129]
	v_lshl_add_u64 v[112:113], v[148:149], 1, v[112:113]
	s_nop 0
	v_pk_mul_f32 v[110:111], v[110:111], v[202:203] op_sel_hi:[1,0]
	v_pk_mul_f32 v[108:109], v[108:109], v[202:203] op_sel_hi:[1,0]
	v_pk_mul_f32 v[114:115], v[106:107], v[202:203] op_sel_hi:[1,0]
	v_pk_mul_f32 v[106:107], v[104:105], v[202:203] op_sel_hi:[1,0]
	v_cvt_pk_bf16_f32 v104, v108, v109
	v_cvt_pk_bf16_f32 v105, v110, v111
	v_pk_mul_f32 v[102:103], v[102:103], v[202:203] op_sel_hi:[1,0]
	v_cvt_pk_bf16_f32 v106, v106, v107
	v_cvt_pk_bf16_f32 v107, v114, v115
	s_waitcnt lgkmcnt(0)
	global_store_dwordx4 v[158:159], v[216:219], off offset:256
	ds_write_b128 v154, v[104:107]
	ds_read_b128 v[216:219], v187
	s_nop 1
	v_pk_mul_f32 v[100:101], v[100:101], v[202:203] op_sel_hi:[1,0]
	s_nop 0
	v_pk_mul_f32 v[104:105], v[98:99], v[202:203] op_sel_hi:[1,0]
	v_pk_mul_f32 v[98:99], v[96:97], v[202:203] op_sel_hi:[1,0]
	v_cvt_pk_bf16_f32 v96, v100, v101
	v_cvt_pk_bf16_f32 v97, v102, v103
	s_nop 0
	v_cvt_pk_bf16_f32 v98, v98, v99
	v_cvt_pk_bf16_f32 v99, v104, v105
	s_waitcnt lgkmcnt(0)
	global_store_dwordx4 v[112:113], v[216:219], off
	ds_write_b128 v154, v[96:99]
	ds_read_b128 v[216:219], v187
	s_nop 1
	s_nop 1
	s_nop 0
	s_nop 0
	s_nop 0
.LBB0_477:
	v_bitop3_b32 v97, v150, s51, 32 bitop3:0xc8
	v_mul_u32_u24_e32 v97, s39, v97
	v_lshlrev_b32_e32 v128, 1, v97
	v_lshl_add_u64 v[100:101], s[88:89], 0, v[128:129]
	v_lshl_add_u64 v[100:101], v[148:149], 1, v[100:101]
	s_nop 0
	v_pk_mul_f32 v[94:95], v[94:95], v[204:205] op_sel_hi:[1,0]
	v_pk_mul_f32 v[92:93], v[92:93], v[204:205] op_sel_hi:[1,0]
	v_pk_mul_f32 v[102:103], v[90:91], v[204:205] op_sel_hi:[1,0]
	v_pk_mul_f32 v[90:91], v[88:89], v[204:205] op_sel_hi:[1,0]
	v_cvt_pk_bf16_f32 v88, v92, v93
	v_cvt_pk_bf16_f32 v89, v94, v95
	s_nop 0
	v_cvt_pk_bf16_f32 v90, v90, v91
	v_cvt_pk_bf16_f32 v91, v102, v103
	s_waitcnt lgkmcnt(0)
	global_store_dwordx4 v[112:113], v[216:219], off offset:256
	ds_write_b128 v154, v[88:91]
	ds_read_b128 v[216:219], v187
	s_nop 1
	v_pk_mul_f32 v[86:87], v[86:87], v[204:205] op_sel_hi:[1,0]
	v_pk_mul_f32 v[84:85], v[84:85], v[204:205] op_sel_hi:[1,0]
	v_pk_mul_f32 v[88:89], v[82:83], v[204:205] op_sel_hi:[1,0]
	v_pk_mul_f32 v[82:83], v[80:81], v[204:205] op_sel_hi:[1,0]
	v_cvt_pk_bf16_f32 v80, v84, v85
	v_cvt_pk_bf16_f32 v81, v86, v87
	s_nop 0
	v_cvt_pk_bf16_f32 v82, v82, v83
	v_cvt_pk_bf16_f32 v83, v88, v89
	s_waitcnt lgkmcnt(0)
	global_store_dwordx4 v[100:101], v[216:219], off
	ds_write_b128 v154, v[80:83]
	ds_read_b128 v[216:219], v187
	s_nop 1
	s_nop 0
.LBB0_479:
	s_movk_i32 s41, 0x7ff
	v_bitop3_b32 v80, v150, s41, 48 bitop3:0xc8
	v_mul_u32_u24_e32 v80, s39, v80
	v_lshlrev_b32_e32 v128, 1, v80
	v_lshl_add_u64 v[80:81], s[88:89], 0, v[128:129]
	v_lshl_add_u64 v[80:81], v[148:149], 1, v[80:81]
	s_nop 0
	v_pk_mul_f32 v[78:79], v[78:79], v[206:207] op_sel_hi:[1,0]
	v_pk_mul_f32 v[76:77], v[76:77], v[206:207] op_sel_hi:[1,0]
	v_pk_mul_f32 v[82:83], v[74:75], v[206:207] op_sel_hi:[1,0]
	v_pk_mul_f32 v[74:75], v[72:73], v[206:207] op_sel_hi:[1,0]
	v_cvt_pk_bf16_f32 v72, v76, v77
	v_cvt_pk_bf16_f32 v73, v78, v79
	v_pk_mul_f32 v[70:71], v[70:71], v[206:207] op_sel_hi:[1,0]
	v_cvt_pk_bf16_f32 v74, v74, v75
	v_cvt_pk_bf16_f32 v75, v82, v83
	s_waitcnt lgkmcnt(0)
	global_store_dwordx4 v[100:101], v[216:219], off offset:256
	ds_write_b128 v154, v[72:75]
	ds_read_b128 v[216:219], v187
	s_nop 1
	v_pk_mul_f32 v[68:69], v[68:69], v[206:207] op_sel_hi:[1,0]
	s_nop 0
	v_pk_mul_f32 v[72:73], v[66:67], v[206:207] op_sel_hi:[1,0]
	v_pk_mul_f32 v[66:67], v[64:65], v[206:207] op_sel_hi:[1,0]
	v_cvt_pk_bf16_f32 v64, v68, v69
	v_cvt_pk_bf16_f32 v65, v70, v71
	s_nop 0
	v_cvt_pk_bf16_f32 v66, v66, v67
	v_cvt_pk_bf16_f32 v67, v72, v73
	s_waitcnt lgkmcnt(0)
	global_store_dwordx4 v[80:81], v[216:219], off
	ds_write_b128 v154, v[64:67]
	ds_read_b128 v[216:219], v187
	s_nop 1
	s_nop 1
	v_add_u32_e32 v64, 0x80, v150
	s_nop 0
	s_nop 0
; __device__ __forceinline__ unsigned cvt_pk_bf16(float lo, float hi) { unsigned r; asm volatile("v_cvt_pk_bf16_f32 %0, %1, %2" : "=v"(r) : "v"(lo), "v"(hi)); return r; }
; __device__ __forceinline__ float relu_sq(float x) { float r; asm volatile("v_max_f32 %0, 0, %1" : "=v"(r) : "v"(x)); return r * r; }
;     __device__ __forceinline__ void operator()(const f32x4 (&acc)[2][2][4][2], const Unit& u, int wr, int wc, int fr, int fq) const {
;     ...
;             for (int m = 0; m < 4; ++m) { const int row_ = row0 + ai * HALF + m * 16; bf16_t* rowp = O + (size_t)(row_ >> 11) * gs + (size_t)(row_ & 2047) * ldc + col0; const float sc = rs ? rs[row0 + ai * HALF + m * 16] : 1.f;
; #pragma unroll
;                 for (int bj = 0; bj < 2; ++bj) { f32x4 v0 = acc[ai][bj][m][0] * sc, v1 = acc[ai][bj][m][1] * sc;
;                     if (ACT == 1) {
; #pragma unroll
;                         for (int e = 0; e < 4; ++e) { v0[e] = relu_sq(v0[e]); v1[e] = relu_sq(v1[e]); } }
;                     u32x4 w; w.x = cvt_pk_bf16(v0[0], v0[1]); w.y = cvt_pk_bf16(v0[2], v0[3]); w.z = cvt_pk_bf16(v1[0], v1[1]); w.w = cvt_pk_bf16(v1[2], v1[3]);
;                     *(u32x4*)(rowp + bj * HALF) = w; } }
.LBB0_481:
	v_and_b32_e32 v67, 0x7cf, v64
	v_ashrrev_i32_e32 v64, 11, v64
	v_mad_i64_i32 v[64:65], s[42:43], s26, v64, 0
	v_mul_u32_u24_e32 v67, s39, v67
	v_lshl_add_u64 v[64:65], v[64:65], 1, s[12:13]
	v_lshlrev_b32_e32 v128, 1, v67
	v_lshl_add_u64 v[70:71], v[64:65], 0, v[128:129]
	v_lshl_add_u64 v[70:71], v[148:149], 1, v[70:71]
	s_nop 0
	v_pk_mul_f32 v[62:63], v[62:63], v[208:209] op_sel_hi:[1,0]
	v_pk_mul_f32 v[60:61], v[60:61], v[208:209] op_sel_hi:[1,0]
	v_pk_mul_f32 v[72:73], v[58:59], v[208:209] op_sel_hi:[1,0]
	v_pk_mul_f32 v[58:59], v[56:57], v[208:209] op_sel_hi:[1,0]
	v_cvt_pk_bf16_f32 v56, v60, v61
	v_cvt_pk_bf16_f32 v57, v62, v63
	v_pk_mul_f32 v[52:53], v[52:53], v[208:209] op_sel_hi:[1,0]
	v_cvt_pk_bf16_f32 v58, v58, v59
	v_cvt_pk_bf16_f32 v59, v72, v73
	s_waitcnt lgkmcnt(0)
	global_store_dwordx4 v[80:81], v[216:219], off offset:256
	ds_write_b128 v154, v[56:59]
	ds_read_b128 v[216:219], v187
	s_nop 1
	v_pk_mul_f32 v[54:55], v[54:55], v[208:209] op_sel_hi:[1,0]
	s_nop 0
	v_pk_mul_f32 v[56:57], v[50:51], v[208:209] op_sel_hi:[1,0]
	v_pk_mul_f32 v[50:51], v[48:49], v[208:209] op_sel_hi:[1,0]
	v_cvt_pk_bf16_f32 v48, v52, v53
	v_cvt_pk_bf16_f32 v49, v54, v55
	s_nop 0
	v_cvt_pk_bf16_f32 v50, v50, v51
	v_cvt_pk_bf16_f32 v51, v56, v57
	s_waitcnt lgkmcnt(0)
	global_store_dwordx4 v[70:71], v[216:219], off
	ds_write_b128 v154, v[48:51]
	ds_read_b128 v[216:219], v187
	s_nop 1
	s_nop 1
	v_add_u32_e32 v48, 0x90, v150
	s_nop 0
.LBB0_483:
	v_and_b32_e32 v48, 0x7df, v48
	v_mul_u32_u24_e32 v48, s39, v48
	v_lshlrev_b32_e32 v128, 1, v48
	v_lshl_add_u64 v[48:49], v[64:65], 0, v[128:129]
	v_lshl_add_u64 v[48:49], v[148:149], 1, v[48:49]
	s_nop 0
	v_pk_mul_f32 v[46:47], v[46:47], v[210:211] op_sel_hi:[1,0]
	v_pk_mul_f32 v[44:45], v[44:45], v[210:211] op_sel_hi:[1,0]
	v_pk_mul_f32 v[50:51], v[42:43], v[210:211] op_sel_hi:[1,0]
	v_pk_mul_f32 v[42:43], v[40:41], v[210:211] op_sel_hi:[1,0]
	v_cvt_pk_bf16_f32 v40, v44, v45
	v_cvt_pk_bf16_f32 v41, v46, v47
	v_pk_mul_f32 v[38:39], v[38:39], v[210:211] op_sel_hi:[1,0]
	v_cvt_pk_bf16_f32 v42, v42, v43
	v_cvt_pk_bf16_f32 v43, v50, v51
	s_waitcnt lgkmcnt(0)
	global_store_dwordx4 v[70:71], v[216:219], off offset:256
	ds_write_b128 v154, v[40:43]
	ds_read_b128 v[216:219], v187
	s_nop 1
	v_pk_mul_f32 v[36:37], v[36:37], v[210:211] op_sel_hi:[1,0]
	s_nop 0
	v_pk_mul_f32 v[40:41], v[34:35], v[210:211] op_sel_hi:[1,0]
	v_pk_mul_f32 v[34:35], v[32:33], v[210:211] op_sel_hi:[1,0]
	v_cvt_pk_bf16_f32 v32, v36, v37
	v_cvt_pk_bf16_f32 v33, v38, v39
	v_add_u32_e32 v36, 0xa0, v150
	v_cvt_pk_bf16_f32 v34, v34, v35
	v_cvt_pk_bf16_f32 v35, v40, v41
	s_waitcnt lgkmcnt(0)
	global_store_dwordx4 v[48:49], v[216:219], off
	ds_write_b128 v154, v[32:35]
	ds_read_b128 v[216:219], v187
	s_nop 1
	s_nop 1
	s_nop 0
	s_nop 0
	s_nop 0
.LBB0_485:
	v_and_b32_e32 v33, 0x7ef, v36
	v_mul_u32_u24_e32 v33, s39, v33
	v_lshlrev_b32_e32 v128, 1, v33
	v_lshl_add_u64 v[36:37], v[64:65], 0, v[128:129]
	v_lshl_add_u64 v[36:37], v[148:149], 1, v[36:37]
	s_nop 0
	v_pk_mul_f32 v[30:31], v[30:31], v[212:213] op_sel_hi:[1,0]
	v_pk_mul_f32 v[28:29], v[28:29], v[212:213] op_sel_hi:[1,0]
	v_pk_mul_f32 v[38:39], v[26:27], v[212:213] op_sel_hi:[1,0]
	v_pk_mul_f32 v[26:27], v[24:25], v[212:213] op_sel_hi:[1,0]
	v_cvt_pk_bf16_f32 v24, v28, v29
	v_cvt_pk_bf16_f32 v25, v30, v31
	v_pk_mul_f32 v[20:21], v[20:21], v[212:213] op_sel_hi:[1,0]
	v_cvt_pk_bf16_f32 v26, v26, v27
	v_cvt_pk_bf16_f32 v27, v38, v39
	s_waitcnt lgkmcnt(0)
	global_store_dwordx4 v[48:49], v[216:219], off offset:256
	ds_write_b128 v154, v[24:27]
	ds_read_b128 v[216:219], v187
	s_nop 1
	v_pk_mul_f32 v[22:23], v[22:23], v[212:213] op_sel_hi:[1,0]
	s_nop 0
	v_pk_mul_f32 v[24:25], v[18:19], v[212:213] op_sel_hi:[1,0]
	v_pk_mul_f32 v[18:19], v[16:17], v[212:213] op_sel_hi:[1,0]
	v_cvt_pk_bf16_f32 v16, v20, v21
	v_cvt_pk_bf16_f32 v17, v22, v23
	s_nop 0
	v_cvt_pk_bf16_f32 v18, v18, v19
	v_cvt_pk_bf16_f32 v19, v24, v25
	s_waitcnt lgkmcnt(0)
	global_store_dwordx4 v[36:37], v[216:219], off
	ds_write_b128 v154, v[16:19]
	ds_read_b128 v[216:219], v187
	s_nop 1
	s_nop 1
	v_add_u32_e32 v16, 0xb0, v150
	s_nop 0
.LBB0_487:
	v_and_b32_e32 v16, 0x7ff, v16
	v_mul_u32_u24_e32 v16, s39, v16
	v_lshlrev_b32_e32 v128, 1, v16
	v_lshl_add_u64 v[16:17], v[64:65], 0, v[128:129]
	v_lshl_add_u64 v[16:17], v[148:149], 1, v[16:17]
	s_nop 0
	v_pk_mul_f32 v[14:15], v[14:15], v[214:215] op_sel_hi:[1,0]
	v_pk_mul_f32 v[12:13], v[12:13], v[214:215] op_sel_hi:[1,0]
	v_pk_mul_f32 v[18:19], v[10:11], v[214:215] op_sel_hi:[1,0]
	v_pk_mul_f32 v[10:11], v[8:9], v[214:215] op_sel_hi:[1,0]
	v_cvt_pk_bf16_f32 v8, v12, v13
	v_cvt_pk_bf16_f32 v9, v14, v15
	s_and_b64 vcc, exec, s[6:7]
	v_cvt_pk_bf16_f32 v10, v10, v11
	v_cvt_pk_bf16_f32 v11, v18, v19
	s_waitcnt lgkmcnt(0)
	global_store_dwordx4 v[36:37], v[216:219], off offset:256
	ds_write_b128 v154, v[8:11]
	ds_read_b128 v[216:219], v187
	s_nop 1
	s_mov_b64 s[6:7], -1
	v_pk_mul_f32 v[6:7], v[6:7], v[214:215] op_sel_hi:[1,0]
	v_pk_mul_f32 v[8:9], v[2:3], v[214:215] op_sel_hi:[1,0]
	v_pk_mul_f32 v[2:3], v[0:1], v[214:215] op_sel_hi:[1,0]
	v_pk_mul_f32 v[4:5], v[4:5], v[214:215] op_sel_hi:[1,0]
	s_nop 0
	v_cvt_pk_bf16_f32 v0, v4, v5
	v_cvt_pk_bf16_f32 v1, v6, v7
	v_cvt_pk_bf16_f32 v2, v2, v3
	v_cvt_pk_bf16_f32 v3, v8, v9
	s_waitcnt lgkmcnt(0)
	global_store_dwordx4 v[16:17], v[216:219], off
	ds_write_b128 v154, v[0:3]
	ds_read_b128 v[216:219], v187
	s_waitcnt lgkmcnt(0)
	global_store_dwordx4 v[16:17], v[216:219], off offset:256
	s_cbranch_vccnz .LBB0_458
	s_andn2_b64 vcc, exec, s[18:19]
	s_cbranch_vccnz .LBB0_457
	s_barrier
	s_branch .LBB0_457
